# FoX QK K-fragment double buffering; GLA-out heads split 3/1 between FoX and MLA workgroups; plus attention half-stagger, scan pipelining
# speedup vs baseline: 1.0202x; 1.0056x over previous
.LBB0_1225:
	ds_read_b128 v[82:85], v195
	ds_read_b128 v[86:89], v195 offset:32
	ds_read_b128 v[66:69], v195 offset:128
	ds_read_b128 v[70:73], v195 offset:160
	ds_read_b128 v[90:93], v195 offset:64
	ds_read_b128 v[74:77], v195 offset:192
	ds_read_b128 v[94:97], v195 offset:96
	ds_read_b128 v[78:81], v195 offset:224
	ds_read_b128 v[202:205], v189 offset:51200
	ds_read_b128 v[206:209], v189 offset:51712
	ds_read_b128 v[238:241], v189 offset:53536
	ds_read_b128 v[242:245], v189 offset:54048
	v_add_f32_e32 v148, 0, v163
	v_add_f32_e32 v148, v177, v148
	v_add_f32_e32 v148, v149, v148
	s_waitcnt lgkmcnt(3)
	v_mfma_f32_32x32x16_bf16 v[82:97], v[202:205], v[128:131], v[82:97]
	v_add_f32_e32 v148, v176, v148
	v_add_f32_e32 v148, v150, v148
	v_add_f32_e32 v148, v162, v148
	v_add_f32_e32 v148, v151, v148
	v_add_f32_e32 v148, v161, v148
	v_add_f32_e32 v148, v152, v148
	v_add_f32_e32 v148, v160, v148
	s_waitcnt lgkmcnt(2)
	v_mfma_f32_32x32x16_bf16 v[66:81], v[206:209], v[128:131], v[66:81]
	ds_read_b128 v[202:205], v189 offset:55872
	ds_read_b128 v[206:209], v189 offset:56384
	v_add_f32_e32 v148, v153, v148
	v_add_f32_e32 v148, v159, v148
	v_exp_f32_e32 v144, v144
	v_add_f32_e32 v148, v154, v148
	v_exp_f32_e32 v145, v145
	v_add_f32_e32 v148, v158, v148
	s_waitcnt lgkmcnt(3)
	v_mfma_f32_32x32x16_bf16 v[82:97], v[238:241], v[124:127], v[82:97]
	v_exp_f32_e32 v142, v142
	v_add_f32_e32 v148, v155, v148
	v_exp_f32_e32 v143, v143
	v_add_f32_e32 v148, v157, v148
	v_exp_f32_e32 v138, v138
	v_add_f32_e32 v148, v144, v148
	v_exp_f32_e32 v139, v139
	s_waitcnt lgkmcnt(2)
	v_mfma_f32_32x32x16_bf16 v[66:81], v[242:245], v[124:127], v[66:81]
	ds_read_b128 v[238:241], v189 offset:58208
	ds_read_b128 v[242:245], v189 offset:58720
	v_add_f32_e32 v148, v145, v148
	v_exp_f32_e32 v136, v136
	v_add_f32_e32 v148, v142, v148
	v_exp_f32_e32 v137, v137
	v_add_f32_e32 v148, v143, v148
	v_exp_f32_e32 v132, v132
	s_waitcnt lgkmcnt(3)
	v_mfma_f32_32x32x16_bf16 v[82:97], v[202:205], v[120:123], v[82:97]
	v_add_f32_e32 v148, v138, v148
	v_exp_f32_e32 v133, v133
	v_add_f32_e32 v148, v139, v148
	v_exp_f32_e32 v146, v146
	v_add_f32_e32 v148, v136, v148
	v_exp_f32_e32 v147, v147
	v_add_f32_e32 v148, v137, v148
	s_waitcnt lgkmcnt(2)
	v_mfma_f32_32x32x16_bf16 v[66:81], v[206:209], v[120:123], v[66:81]
	ds_read_b128 v[202:205], v189 offset:60416
	ds_read_b128 v[206:209], v189 offset:60928
	v_exp_f32_e32 v140, v140
	v_add_f32_e32 v148, v132, v148
	v_exp_f32_e32 v141, v141
	v_add_f32_e32 v148, v133, v148
	v_exp_f32_e32 v134, v134
	v_add_f32_e32 v148, v146, v148
	s_waitcnt lgkmcnt(3)
	v_mfma_f32_32x32x16_bf16 v[82:97], v[238:241], v[116:119], v[82:97]
	v_exp_f32_e32 v135, v135
	v_add_f32_e32 v148, v147, v148
	v_add_f32_e32 v148, v140, v148
	v_add_f32_e32 v148, v141, v148
	v_add_f32_e32 v148, v134, v148
	v_add_f32_e32 v197, v135, v148
	v_mov_b32_e32 v198, v197
	s_waitcnt lgkmcnt(2)
	v_mfma_f32_32x32x16_bf16 v[66:81], v[242:245], v[116:119], v[66:81]
	ds_read_b128 v[238:241], v189 offset:62752
	ds_read_b128 v[242:245], v189 offset:63264
	v_permlane32_swap_b32_e32 v197, v198
	s_waitcnt lgkmcnt(3)
	v_mfma_f32_32x32x16_bf16 v[82:97], v[202:205], v[112:115], v[82:97]
	s_waitcnt lgkmcnt(2)
	v_mfma_f32_32x32x16_bf16 v[66:81], v[206:209], v[112:115], v[66:81]
	ds_read_b128 v[202:205], v189 offset:65088
	ds_read_b128 v[206:209], v193 offset:14400
	s_waitcnt lgkmcnt(3)
	v_mfma_f32_32x32x16_bf16 v[82:97], v[238:241], v[108:111], v[82:97]
	s_waitcnt lgkmcnt(2)
	v_mfma_f32_32x32x16_bf16 v[66:81], v[242:245], v[108:111], v[66:81]
	ds_read_b128 v[238:241], v193 offset:16224
	ds_read_b128 v[242:245], v193 offset:16736
	s_waitcnt lgkmcnt(3)
	v_mfma_f32_32x32x16_bf16 v[82:97], v[202:205], v[104:107], v[82:97]
	s_waitcnt lgkmcnt(2)
	v_mfma_f32_32x32x16_bf16 v[66:81], v[206:209], v[104:107], v[66:81]
	v_cvt_pk_bf16_f32 v148, v163, v177
	v_cvt_pk_bf16_f32 v149, v149, v176
	v_cvt_pk_bf16_f32 v150, v150, v162
	v_cvt_pk_bf16_f32 v151, v151, v161
	v_cvt_pk_bf16_f32 v152, v152, v160
	v_cvt_pk_bf16_f32 v153, v153, v159
	s_waitcnt lgkmcnt(1)
	v_mfma_f32_32x32x16_bf16 v[82:97], v[238:241], v[100:103], v[82:97]
	v_cvt_pk_bf16_f32 v154, v154, v158
	v_cvt_pk_bf16_f32 v155, v155, v157
	v_cvt_pk_bf16_f32 v158, v144, v145
	v_cvt_pk_bf16_f32 v159, v142, v143
	v_cvt_pk_bf16_f32 v160, v138, v139
	v_cvt_pk_bf16_f32 v161, v136, v137
	v_cvt_pk_bf16_f32 v202, v132, v133
	s_waitcnt lgkmcnt(0)
	v_mfma_f32_32x32x16_bf16 v[66:81], v[242:245], v[100:103], v[66:81]
	v_cvt_pk_bf16_f32 v203, v146, v147
	v_cvt_pk_bf16_f32 v204, v140, v141
	v_cvt_pk_bf16_f32 v205, v134, v135
	v_permlane32_swap_b32_e32 v148, v150
	v_permlane32_swap_b32_e32 v149, v151
	v_permlane32_swap_b32_e32 v152, v154
	v_permlane32_swap_b32_e32 v153, v155
	v_permlane32_swap_b32_e32 v158, v160
	v_permlane32_swap_b32_e32 v159, v161
	v_permlane32_swap_b32_e32 v202, v204
	v_permlane32_swap_b32_e32 v203, v205
	v_lshl_add_u64 v[178:179], v[174:175], 0, v[98:99]
	s_mov_b32 s4, 0x24053000
	v_add_co_u32_e32 v132, vcc, s4, v178
	s_mov_b32 s4, 0x24127000
	s_nop 0
	v_addc_co_u32_e32 v133, vcc, 0, v179, vcc
	v_add_co_u32_e32 v136, vcc, s4, v178
	v_lshl_add_u64 v[176:177], v[172:173], 0, v[98:99]
	s_nop 0
	v_addc_co_u32_e32 v137, vcc, 0, v179, vcc
	s_mov_b32 s4, 0x40108000
	v_add_co_u32_e32 v140, vcc, s4, v176
	s_mov_b32 s4, 0x4010a000
	s_nop 0
	v_addc_co_u32_e32 v141, vcc, 0, v177, vcc
	v_add_co_u32_e32 v144, vcc, s4, v176
	global_load_dwordx4 v[132:135], v[132:133], off
	s_nop 0
	global_load_dwordx4 v[136:139], v[136:137], off
	v_addc_co_u32_e32 v145, vcc, 0, v177, vcc
	global_load_dwordx4 v[140:143], v[140:141], off
	s_nop 0
	global_load_dwordx4 v[144:147], v[144:145], off
	ds_read_b64_tr_b16 v[206:207], v167 offset:0
	ds_read_b64_tr_b16 v[208:209], v167 offset:0x800
	ds_read_b64_tr_b16 v[210:211], v167 offset:0x1000
	ds_read_b64_tr_b16 v[212:213], v167 offset:0x1800
	ds_read_b64_tr_b16 v[214:215], v167 offset:0x2000
	ds_read_b64_tr_b16 v[216:217], v167 offset:0x2800
	ds_read_b64_tr_b16 v[218:219], v167 offset:0x3000
	ds_read_b64_tr_b16 v[220:221], v167 offset:0x3800
	s_waitcnt lgkmcnt(0)
	s_nop 0
	v_mfma_f32_32x32x16_bf16 v[34:49], v[148:151], v[206:209], v[34:49]
	ds_read_b64_tr_b16 v[206:207], v167 offset:0x200
	ds_read_b64_tr_b16 v[208:209], v167 offset:0xa00
	v_mfma_f32_32x32x16_bf16 v[34:49], v[152:155], v[210:213], v[34:49]
	ds_read_b64_tr_b16 v[210:211], v167 offset:0x1200
	ds_read_b64_tr_b16 v[212:213], v167 offset:0x1a00
	v_mfma_f32_32x32x16_bf16 v[34:49], v[158:161], v[214:217], v[34:49]
	ds_read_b64_tr_b16 v[214:215], v167 offset:0x2200
	ds_read_b64_tr_b16 v[216:217], v167 offset:0x2a00
	v_mfma_f32_32x32x16_bf16 v[34:49], v[202:205], v[218:221], v[34:49]
	ds_read_b64_tr_b16 v[218:219], v167 offset:0x3200
	ds_read_b64_tr_b16 v[220:221], v167 offset:0x3a00
	s_waitcnt lgkmcnt(0)
	v_mfma_f32_32x32x16_bf16 v[50:65], v[148:151], v[206:209], v[50:65]
	ds_read_b64_tr_b16 v[206:207], v167 offset:0x400
	ds_read_b64_tr_b16 v[208:209], v167 offset:0xc00
	v_mfma_f32_32x32x16_bf16 v[50:65], v[152:155], v[210:213], v[50:65]
	ds_read_b64_tr_b16 v[210:211], v167 offset:0x1400
	ds_read_b64_tr_b16 v[212:213], v167 offset:0x1c00
	v_mfma_f32_32x32x16_bf16 v[50:65], v[158:161], v[214:217], v[50:65]
	ds_read_b64_tr_b16 v[214:215], v167 offset:0x2400
	ds_read_b64_tr_b16 v[216:217], v167 offset:0x2c00
	v_mfma_f32_32x32x16_bf16 v[50:65], v[202:205], v[218:221], v[50:65]
	ds_read_b64_tr_b16 v[218:219], v167 offset:0x3400
	ds_read_b64_tr_b16 v[220:221], v167 offset:0x3c00
	s_waitcnt lgkmcnt(0)
	v_mfma_f32_32x32x16_bf16 v[18:33], v[148:151], v[206:209], v[18:33]
	ds_read_b64_tr_b16 v[206:207], v167 offset:0x600
	ds_read_b64_tr_b16 v[208:209], v167 offset:0xe00
	v_mfma_f32_32x32x16_bf16 v[18:33], v[152:155], v[210:213], v[18:33]
	ds_read_b64_tr_b16 v[210:211], v167 offset:0x1600
	ds_read_b64_tr_b16 v[212:213], v167 offset:0x1e00
	v_mfma_f32_32x32x16_bf16 v[18:33], v[158:161], v[214:217], v[18:33]
	ds_read_b64_tr_b16 v[214:215], v167 offset:0x2600
	ds_read_b64_tr_b16 v[216:217], v167 offset:0x2e00
	v_mfma_f32_32x32x16_bf16 v[18:33], v[202:205], v[218:221], v[18:33]
	ds_read_b64_tr_b16 v[218:219], v167 offset:0x3600
	ds_read_b64_tr_b16 v[220:221], v167 offset:0x3e00
	s_waitcnt lgkmcnt(0)
	v_mfma_f32_32x32x16_bf16 v[2:17], v[148:151], v[206:209], v[2:17]
	s_sub_i32 s4, s11, 64
	s_cmp_le_i32 s4, s68
	v_mfma_f32_32x32x16_bf16 v[2:17], v[152:155], v[210:213], v[2:17]
	v_mfma_f32_32x32x16_bf16 v[2:17], v[158:161], v[214:217], v[2:17]
	v_mfma_f32_32x32x16_bf16 v[2:17], v[202:205], v[218:221], v[2:17]
	s_cbranch_scc1 .LBB0_1227
	v_add_u32_e32 v148, 64, v196
	v_cmp_gt_i32_e64 s[94:95], 26, v148
	v_cmp_gt_i32_e64 s[96:97], 27, v148
	v_cmp_gt_i32_e64 s[92:93], 25, v148
	s_and_b64 s[94:95], s[96:97], s[94:95]
	v_cmp_gt_i32_e64 s[90:91], 24, v148
	s_and_b64 s[92:93], s[94:95], s[92:93]
	v_cmp_gt_i32_e64 s[88:89], 19, v148
	s_and_b64 s[90:91], s[92:93], s[90:91]
	v_cmp_gt_i32_e64 s[86:87], 18, v148
	s_and_b64 s[88:89], s[90:91], s[88:89]
	v_cmp_gt_i32_e64 s[84:85], 17, v148
	s_and_b64 s[86:87], s[88:89], s[86:87]
	v_cmp_gt_i32_e64 s[82:83], 16, v148
	s_and_b64 s[84:85], s[86:87], s[84:85]
	v_cmp_gt_i32_e64 s[80:81], 11, v148
	s_and_b64 s[82:83], s[84:85], s[82:83]
	v_cmp_gt_i32_e64 s[78:79], 10, v148
	s_and_b64 s[80:81], s[82:83], s[80:81]
	v_cmp_gt_i32_e64 s[76:77], 9, v148
	s_and_b64 s[78:79], s[80:81], s[78:79]
	v_cmp_gt_i32_e64 s[74:75], 8, v148
	s_and_b64 s[76:77], s[78:79], s[76:77]
	v_cmp_gt_i32_e64 s[72:73], 3, v148
	s_and_b64 s[74:75], s[76:77], s[74:75]
	v_cmp_gt_i32_e64 s[70:71], 2, v148
	s_and_b64 s[72:73], s[74:75], s[72:73]
	v_cmp_gt_i32_e64 s[6:7], 1, v148
	s_and_b64 s[70:71], s[72:73], s[70:71]
	v_cmp_gt_i32_e64 s[4:5], 0, v148
	s_and_b64 s[6:7], s[70:71], s[6:7]
	s_and_b64 s[4:5], s[6:7], s[4:5]
	v_cmp_gt_i32_e64 s[66:67], 58, v148
	v_cndmask_b32_e64 v82, v82, v236, s[4:5]
	v_cmp_gt_i32_e64 s[4:5], 59, v148
	v_cmp_gt_i32_e64 s[64:65], 57, v148
	v_cmp_gt_i32_e64 s[62:63], 56, v148
	v_cndmask_b32_e64 v81, v81, v236, s[4:5]
	s_and_b64 s[4:5], s[4:5], s[66:67]
	v_cndmask_b32_e64 v80, v80, v236, s[4:5]
	s_and_b64 s[4:5], s[4:5], s[64:65]
	v_cmp_gt_i32_e64 s[60:61], 51, v148
	v_cndmask_b32_e64 v79, v79, v236, s[4:5]
	s_and_b64 s[4:5], s[4:5], s[62:63]
	v_cmp_gt_i32_e64 s[58:59], 50, v148
	v_cndmask_b32_e64 v78, v78, v236, s[4:5]
	s_and_b64 s[4:5], s[4:5], s[60:61]
	v_cmp_gt_i32_e64 s[56:57], 49, v148
	v_cndmask_b32_e64 v77, v77, v236, s[4:5]
	s_and_b64 s[4:5], s[4:5], s[58:59]
	v_cmp_gt_i32_e64 s[54:55], 48, v148
	v_cndmask_b32_e64 v76, v76, v236, s[4:5]
	s_and_b64 s[4:5], s[4:5], s[56:57]
	v_cmp_gt_i32_e64 s[52:53], 43, v148
	v_cndmask_b32_e64 v75, v75, v236, s[4:5]
	s_and_b64 s[4:5], s[4:5], s[54:55]
	v_cmp_gt_i32_e64 s[50:51], 42, v148
	v_cndmask_b32_e64 v74, v74, v236, s[4:5]
	s_and_b64 s[4:5], s[4:5], s[52:53]
	v_cmp_gt_i32_e64 s[48:49], 41, v148
	v_cndmask_b32_e64 v73, v73, v236, s[4:5]
	s_and_b64 s[4:5], s[4:5], s[50:51]
	v_cmp_gt_i32_e64 s[46:47], 40, v148
	v_cndmask_b32_e64 v72, v72, v236, s[4:5]
	s_and_b64 s[4:5], s[4:5], s[48:49]
	v_cmp_gt_i32_e64 s[44:45], 35, v148
	v_cndmask_b32_e64 v71, v71, v236, s[4:5]
	s_and_b64 s[4:5], s[4:5], s[46:47]
	v_cmp_gt_i32_e64 s[42:43], 34, v148
	v_cndmask_b32_e64 v70, v70, v236, s[4:5]
	s_and_b64 s[4:5], s[4:5], s[44:45]
	v_cmp_gt_i32_e64 s[40:41], 33, v148
	v_cndmask_b32_e64 v69, v69, v236, s[4:5]
	s_and_b64 s[4:5], s[4:5], s[42:43]
	v_cmp_gt_i32_e32 vcc, 32, v148
	v_cndmask_b32_e64 v68, v68, v236, s[4:5]
	s_and_b64 s[4:5], s[4:5], s[40:41]
	s_and_b64 vcc, s[4:5], vcc
	v_cndmask_b32_e64 v97, v97, v236, s[96:97]
	v_cndmask_b32_e64 v96, v96, v236, s[94:95]
	v_cndmask_b32_e64 v95, v95, v236, s[92:93]
	v_cndmask_b32_e64 v94, v94, v236, s[90:91]
	v_cndmask_b32_e64 v93, v93, v236, s[88:89]
	v_cndmask_b32_e64 v92, v92, v236, s[86:87]
	v_cndmask_b32_e64 v91, v91, v236, s[84:85]
	v_cndmask_b32_e64 v90, v90, v236, s[82:83]
	v_cndmask_b32_e64 v89, v89, v236, s[80:81]
	v_cndmask_b32_e64 v88, v88, v236, s[78:79]
	v_cndmask_b32_e64 v87, v87, v236, s[76:77]
	v_cndmask_b32_e64 v86, v86, v236, s[74:75]
	v_cndmask_b32_e64 v85, v85, v236, s[72:73]
	v_cndmask_b32_e64 v84, v84, v236, s[70:71]
	v_cndmask_b32_e64 v83, v83, v236, s[6:7]
	v_cndmask_b32_e64 v67, v67, v236, s[4:5]
	v_cndmask_b32_e32 v66, v66, v236, vcc

.Lblk2_j:
	ds_read_b128 v[82:85], v195 offset:256
	ds_read_b128 v[86:89], v195 offset:288
	ds_read_b128 v[66:69], v195 offset:384
	ds_read_b128 v[70:73], v195 offset:416
	ds_read_b128 v[90:93], v195 offset:320
	ds_read_b128 v[74:77], v195 offset:448
	ds_read_b128 v[94:97], v195 offset:352
	ds_read_b128 v[78:81], v195 offset:480
	ds_read_b128 v[202:205], v189 offset:32768
	ds_read_b128 v[222:225], v189 offset:33280
	ds_read_b128 v[238:241], v189 offset:35104
	ds_read_b128 v[242:245], v189 offset:35616
	v_exp_f32_e32 v208, v208
	v_exp_f32_e32 v209, v209
	v_exp_f32_e32 v210, v210
	s_waitcnt lgkmcnt(3)
	v_mfma_f32_32x32x16_bf16 v[82:97], v[202:205], v[128:131], v[82:97]
	v_exp_f32_e32 v211, v211
	v_exp_f32_e32 v212, v212
	v_exp_f32_e32 v213, v213
	v_exp_f32_e32 v214, v214
	s_waitcnt lgkmcnt(2)
	v_mfma_f32_32x32x16_bf16 v[66:81], v[222:225], v[128:131], v[66:81]
	ds_read_b128 v[202:205], v189 offset:37440
	ds_read_b128 v[222:225], v189 offset:37952
	s_waitcnt lgkmcnt(3)
	v_mfma_f32_32x32x16_bf16 v[82:97], v[238:241], v[124:127], v[82:97]
	s_waitcnt lgkmcnt(2)
	v_mfma_f32_32x32x16_bf16 v[66:81], v[242:245], v[124:127], v[66:81]
	ds_read_b128 v[238:241], v189 offset:39776
	ds_read_b128 v[242:245], v189 offset:40288
	s_waitcnt lgkmcnt(3)
	v_mfma_f32_32x32x16_bf16 v[82:97], v[202:205], v[120:123], v[82:97]
	s_waitcnt lgkmcnt(2)
	v_mfma_f32_32x32x16_bf16 v[66:81], v[222:225], v[120:123], v[66:81]
	ds_read_b128 v[202:205], v189 offset:41984
	ds_read_b128 v[222:225], v189 offset:42496
	s_waitcnt lgkmcnt(3)
	v_mfma_f32_32x32x16_bf16 v[82:97], v[238:241], v[116:119], v[82:97]
	s_waitcnt lgkmcnt(2)
	v_mfma_f32_32x32x16_bf16 v[66:81], v[242:245], v[116:119], v[66:81]
	ds_read_b128 v[238:241], v189 offset:44320
	ds_read_b128 v[242:245], v189 offset:44832
	s_waitcnt lgkmcnt(3)
	v_mfma_f32_32x32x16_bf16 v[82:97], v[202:205], v[112:115], v[82:97]
	s_waitcnt lgkmcnt(2)
	v_mfma_f32_32x32x16_bf16 v[66:81], v[222:225], v[112:115], v[66:81]
	ds_read_b128 v[202:205], v189 offset:46656
	ds_read_b128 v[222:225], v189 offset:47168
	s_waitcnt lgkmcnt(3)
	v_mfma_f32_32x32x16_bf16 v[82:97], v[238:241], v[108:111], v[82:97]
	s_waitcnt lgkmcnt(2)
	v_mfma_f32_32x32x16_bf16 v[66:81], v[242:245], v[108:111], v[66:81]
	ds_read_b128 v[238:241], v189 offset:48992
	ds_read_b128 v[242:245], v189 offset:49504
	s_waitcnt lgkmcnt(3)
	v_mfma_f32_32x32x16_bf16 v[82:97], v[202:205], v[104:107], v[82:97]
	s_waitcnt lgkmcnt(2)
	v_mfma_f32_32x32x16_bf16 v[66:81], v[222:225], v[104:107], v[66:81]
	s_waitcnt lgkmcnt(1)
	v_mfma_f32_32x32x16_bf16 v[82:97], v[238:241], v[100:103], v[82:97]
	v_exp_f32_e32 v202, v215
	v_exp_f32_e32 v215, v219
	v_exp_f32_e32 v219, v206
	v_add_f32_e32 v206, 0, v148
	v_add_f32_e32 v206, v163, v206
	v_add_f32_e32 v206, v149, v206
	v_add_f32_e32 v206, v162, v206
	v_add_f32_e32 v206, v150, v206
	v_add_f32_e32 v206, v161, v206
	v_add_f32_e32 v206, v151, v206
	v_add_f32_e32 v206, v160, v206
	v_add_f32_e32 v206, v152, v206
	v_add_f32_e32 v206, v159, v206
	v_add_f32_e32 v206, v153, v206
	v_add_f32_e32 v206, v158, v206
	v_add_f32_e32 v206, v154, v206
	v_exp_f32_e32 v203, v216
	v_add_f32_e32 v206, v157, v206
	v_exp_f32_e32 v204, v217
	v_add_f32_e32 v206, v155, v206
	v_exp_f32_e32 v205, v218
	v_add_f32_e32 v206, v156, v206
	v_add_f32_e32 v206, v202, v206
	v_add_f32_e32 v206, v203, v206
	v_add_f32_e32 v206, v204, v206
	v_add_f32_e32 v206, v205, v206
	v_add_f32_e32 v206, v215, v206
	v_add_f32_e32 v206, v208, v206
	v_add_f32_e32 v206, v209, v206
	v_add_f32_e32 v206, v210, v206
	v_exp_f32_e32 v216, v207
	v_add_f32_e32 v206, v211, v206
	v_exp_f32_e32 v217, v220
	v_add_f32_e32 v206, v212, v206
	s_waitcnt lgkmcnt(0)
	v_mfma_f32_32x32x16_bf16 v[66:81], v[242:245], v[100:103], v[66:81]
	v_exp_f32_e32 v218, v221
	v_add_f32_e32 v206, v213, v206
	v_add_f32_e32 v206, v214, v206
	v_add_f32_e32 v206, v216, v206
	v_add_f32_e32 v206, v217, v206
	v_add_f32_e32 v206, v218, v206
	v_add_f32_e32 v206, v219, v206
	v_mov_b32_e32 v207, v206
	v_cvt_pk_bf16_f32 v148, v148, v163
	v_cvt_pk_bf16_f32 v149, v149, v162
	v_cvt_pk_bf16_f32 v150, v150, v161
	v_cvt_pk_bf16_f32 v151, v151, v160
	v_cvt_pk_bf16_f32 v152, v152, v159
	v_cvt_pk_bf16_f32 v153, v153, v158
	v_cvt_pk_bf16_f32 v154, v154, v157
	v_cvt_pk_bf16_f32 v155, v155, v156
	v_cvt_pk_bf16_f32 v156, v202, v203
	v_cvt_pk_bf16_f32 v157, v204, v205
	v_cvt_pk_bf16_f32 v158, v215, v208
	v_cvt_pk_bf16_f32 v159, v209, v210
	v_cvt_pk_bf16_f32 v160, v211, v212
	v_cvt_pk_bf16_f32 v161, v213, v214
	v_cvt_pk_bf16_f32 v162, v216, v217
	v_cvt_pk_bf16_f32 v163, v218, v219
	s_nop 1
	v_permlane32_swap_b32_e32 v206, v207
	v_permlane32_swap_b32_e32 v148, v150
	v_permlane32_swap_b32_e32 v149, v151
	v_permlane32_swap_b32_e32 v152, v154
	v_permlane32_swap_b32_e32 v153, v155
	v_permlane32_swap_b32_e32 v156, v158
	v_permlane32_swap_b32_e32 v157, v159
	v_permlane32_swap_b32_e32 v160, v162
	v_permlane32_swap_b32_e32 v161, v163
	s_add_i32 s4, s0, 1
	s_cmp_lt_u32 s4, s35
	s_cselect_b64 s[24:25], -1, 0
	s_cmp_ge_u32 s4, s35
	s_cbranch_scc1 .LBB0_1233
	v_add_co_u32_e32 v132, vcc, 0x241fb000, v178
	s_nop 1
	v_addc_co_u32_e32 v133, vcc, 0, v179, vcc
	v_add_co_u32_e32 v136, vcc, 0x242cf000, v178
	s_nop 1
	v_addc_co_u32_e32 v137, vcc, 0, v179, vcc
	v_add_co_u32_e32 v140, vcc, 0x4010c000, v176
	global_load_dwordx4 v[132:135], v[132:133], off
	s_nop 0
	global_load_dwordx4 v[136:139], v[136:137], off
	v_addc_co_u32_e32 v141, vcc, 0, v177, vcc
	v_add_co_u32_e32 v144, vcc, 0x4010e000, v176
	s_nop 1
	v_addc_co_u32_e32 v145, vcc, 0, v177, vcc
	global_load_dwordx4 v[140:143], v[140:141], off
	s_nop 0
	global_load_dwordx4 v[144:147], v[144:145], off

.LBB0_1544:
	v_readlane_b32 s10, v254, 13
	v_readlane_b32 s11, v254, 14
	s_cmpk_lt_i32 s3, 0x80
	s_cselect_b32 s100, 1, 0
	s_bfe_u32 s9, s60, 0x30004
	s_bfe_u32 s13, s3, 0x40003
	s_lshl_b32 s12, s9, 10
	s_lshl_b32 s14, s13, 6
	s_or_b32 s14, s12, s14
	s_lshl_b32 s12, s9, 14
	s_lshl_b32 s15, s13, 10
	s_mul_i32 s9, s9, 0x1a80000
	s_mul_i32 s13, s13, 0x1a8000
	s_lshl_b32 s43, s14, 10
	s_or_b32 s66, s12, s15
	s_add_i32 s67, s9, s13
	s_load_dwordx2 s[12:13], s[10:11], 0x60
	s_load_dwordx2 s[50:51], s[10:11], 0xb0
	s_add_u32 s69, s44, s67
	s_addc_u32 s70, s45, 0
	s_add_u32 s71, s46, s67
	s_addc_u32 s72, s47, 0
	s_waitcnt lgkmcnt(0)
	s_add_u32 s52, s12, s48
	s_addc_u32 s53, s13, s49
	s_add_u32 s54, s50, 0x46300000
	s_mov_b32 s65, s8
	s_mov_b32 s68, s8
	s_addc_u32 s55, s51, 0
	s_or_b32 s73, s14, s62
	s_or_b32 s74, s14, s63
	s_or_b32 s75, s14, s64
	s_or_b32 s76, s14, s31
	s_mov_b64 s[56:57], 0
	s_movk_i32 s101, 0x600
	s_cmp_eq_u32 s100, 0
	s_cbranch_scc1 .Lgs_fox
	s_movk_i32 s101, 0x800
	s_movk_i32 s56, 0x600
	s_add_u32 s43, s43, 0x300
	s_addc_u32 s65, s65, 0
	s_addk_i32 s66, 0x300
	s_add_u32 s69, s69, 0x600
	s_addc_u32 s70, s70, 0
	s_add_u32 s71, s71, 0x600
	s_addc_u32 s72, s72, 0
	s_add_u32 s67, s67, 0x600
	s_addc_u32 s68, s68, 0

.LBB0_1546:
	s_or_b64 exec, exec, s[10:11]
	s_add_u32 s56, s56, 0x200
	s_addc_u32 s57, s57, 0
	s_add_u32 s43, s43, 0x100
	s_addc_u32 s65, s65, 0
	s_addk_i32 s66, 0x100
	s_add_u32 s69, s69, 0x200
	s_addc_u32 s70, s70, 0
	s_add_u32 s71, s71, 0x200
	s_addc_u32 s72, s72, 0
	s_add_u32 s67, s67, 0x200
	s_addc_u32 s68, s68, 0
	s_cmp_lg_u32 s56, s101
	s_cbranch_scc0 .LBB0_1542
